# v12: v8 + XCD-group phase desync in P2 (XCDs4-7 run B,C before A)
# baseline (speedup 1.0000x reference)
; __global__ void __launch_bounds__(NTHREADS, 2) hymba_fwd(Args args) {
;     ...
;     if (tid < 2) barst[tid] = 0u;
;     __syncthreads();
;     { CArgsP ap0 = (CArgsP)__builtin_amdgcn_kernarg_segment_ptr(); (void)xcd_barrier_post((unsigned*)(ap0->ws + WS_BAR), barst, tid == 0); }
.LBB0_3:
	s_or_b64 exec, exec, s[2:3]
	v_mov_b32_e32 v1, 0x20208
	v_mov_b32_e32 v2, 0
	ds_write_b32 v1, v2
	s_waitcnt lgkmcnt(0)
	s_barrier
	v_cmp_eq_u32_e32 vcc, 0, v31
	s_getreg_b32 s6, hwreg(HW_REG_XCC_ID, 0, 4)
	s_and_saveexec_b64 s[2:3], vcc
	s_cbranch_execz .LBB0_6
	s_mov_b64 s[4:5], exec
	v_mbcnt_lo_u32_b32 v1, s4, 0
	v_mbcnt_hi_u32_b32 v1, s5, v1
	v_cmp_eq_u32_e32 vcc, 0, v1
	s_and_b64 s[8:9], exec, vcc
	s_mov_b64 exec, s[8:9]
	s_cbranch_execz .LBB0_6
	v_readlane_b32 s0, v254, 0
	v_readlane_b32 s1, v254, 1
	s_load_dwordx2 s[8:9], s[0:1], 0xe0
	s_lshl_b32 s6, s6, 8
	s_and_b32 s6, s6, 0xf00
	v_mov_b32_e32 v1, 0x3480000
	s_waitcnt lgkmcnt(0)
	s_add_u32 s6, s8, s6
	s_addc_u32 s7, s9, 0
	s_bcnt1_i32_b64 s4, s[4:5]
	v_mov_b32_e32 v2, s4
	global_atomic_add v1, v2, s[6:7] offset:1024

; __device__ __forceinline__ int fresh_tid(int wave) { int z = 0; asm volatile("" : "+v"(z)); return wave * 64 + (int)__builtin_amdgcn_mbcnt_hi(~0u, __builtin_amdgcn_mbcnt_lo(~0u, (unsigned)z)); }
; __global__ void __launch_bounds__(NTHREADS, 2) hymba_fwd(Args args) {
;     ...
;         {
;             PHASE_ENV
;             float* lutA = (float*)(lds + att::OFF_LUTA); float* lutB = (float*)(lds + att::OFF_LUTB); float* misc = (float*)(lds + att::OFF_MISC);
;             int t2 = fresh_tid(wave); asm volatile("" : "+v"(t2));
;             for (int i = t2; i < 4 * 641; i += NTHREADS) { const int h = i / 641, x = i - h * 641; lutA[h * att::LUTA_STRIDE + x] = ap_->in[I_RELB][t5_bucket(x - 320) * 4 + h] * LOG2E; }
;             for (int i = t2; i < 4 * 15 * 128; i += NTHREADS) { const int x = i & 127, hd = i >> 7, dc = x - 49; lutB[i] = (dc >= 0 && dc <= 30) ? ap_->in[I_NAB][(size_t)l * 4 * 15 * 31 + hd * 31 + dc] * LOG2E : 0.f; }
.Lp2_reenter:
	v_mov_b32_e32 v0, 0x20208
	ds_read_b32 v1, v0
	s_waitcnt lgkmcnt(0)
	v_readfirstlane_b32 s0, v1
	s_nop 3
	s_cmp_eq_u32 s0, 2
	s_cbranch_scc1 .Lp2_restore19
	v_writelane_b32 v253, s36, 0
	v_writelane_b32 v253, s37, 1
	v_writelane_b32 v253, s50, 2
	v_writelane_b32 v253, s51, 3
	v_writelane_b32 v253, s52, 4
	v_writelane_b32 v253, s53, 5
	v_writelane_b32 v253, s54, 6
	v_writelane_b32 v253, s59, 7
	v_writelane_b32 v253, s60, 8
	v_writelane_b32 v253, s61, 9
	v_writelane_b32 v253, s64, 10
	v_writelane_b32 v253, s67, 11
	v_writelane_b32 v253, s68, 12
	v_writelane_b32 v253, s69, 13
	v_writelane_b32 v253, s72, 14
	v_writelane_b32 v253, s78, 15
	v_writelane_b32 v253, s79, 16
	v_writelane_b32 v253, s81, 17
	v_writelane_b32 v253, s85, 18
	s_branch .Lp2_pa_done
.Lp2_restore19:
	v_readlane_b32 s36, v253, 0
	v_readlane_b32 s37, v253, 1
	v_readlane_b32 s50, v253, 2
	v_readlane_b32 s51, v253, 3
	v_readlane_b32 s52, v253, 4
	v_readlane_b32 s53, v253, 5
	v_readlane_b32 s54, v253, 6
	v_readlane_b32 s59, v253, 7
	v_readlane_b32 s60, v253, 8
	v_readlane_b32 s61, v253, 9
	v_readlane_b32 s64, v253, 10
	v_readlane_b32 s67, v253, 11
	v_readlane_b32 s68, v253, 12
	v_readlane_b32 s69, v253, 13
	v_readlane_b32 s72, v253, 14
	v_readlane_b32 s78, v253, 15
	v_readlane_b32 s79, v253, 16
	v_readlane_b32 s81, v253, 17
	v_readlane_b32 s85, v253, 18
	s_nop 4
.Lp2_pa_done:
	v_readlane_b32 s2, v254, 0
	v_readlane_b32 s3, v254, 1
	s_waitcnt lgkmcnt(0)
	v_mov_b32_e32 v0, v145
	s_barrier
	s_load_dwordx2 s[16:17], s[2:3], 0xe0
	s_movk_i32 s0, 0xa04
	v_mbcnt_lo_u32_b32 v0, -1, v0
	v_mbcnt_hi_u32_b32 v0, -1, v0
	v_add_u32_e32 v0, s81, v0
	s_nop 0
	v_cmp_gt_i32_e32 vcc, s0, v0
	s_and_saveexec_b64 s[6:7], vcc
	s_cbranch_execz .LBB0_288
	s_load_dwordx2 s[8:9], s[2:3], 0x68
	v_max_i32_e32 v1, 0x804, v0
	v_sub_u32_e32 v1, v1, v0
	v_add_u32_e32 v2, 0x1ff, v1
	s_movk_i32 s0, 0x1ff
	v_cmp_lt_u32_e32 vcc, s0, v2
	s_mov_b64 s[4:5], -1
	v_mov_b32_e32 v1, v0
	s_and_saveexec_b64 s[10:11], vcc
	s_cbranch_execz .LBB0_281
	v_lshrrev_b32_e32 v1, 9, v2
	v_add_u32_e32 v4, 1, v1
	v_and_b32_e32 v5, 0xfffffe, v4
	v_add_u32_e32 v1, 0x200, v0
	s_mov_b64 s[12:13], 0
	v_mov_b32_e32 v6, v5
	v_mov_b64_e32 v[2:3], v[0:1]

; #define SGPRF(x) __builtin_bit_cast(float, __builtin_amdgcn_readfirstlane(__builtin_bit_cast(int, (float)(x))))
; __global__ void __launch_bounds__(NTHREADS, 2) hymba_fwd(Args args) {
;     ...
;             __syncthreads();
;     ...
;             const float lam = SGPRF(misc[0]), oscale = SGPRF(misc[1]), mshA = SGPRF(misc[2]), mshB = SGPRF(misc[3]), mshC = SGPRF(misc[4]);
;             att::UnitArgs U;
;             U.subg = ap_->in[I_SUBG] + l * 128; U.lam = lam; U.oscale = oscale; U.tile0 = 0; U.R = 0;
;             for (int u = vcu; u < 2560; u += G) {
;                 int h, qblk, S_; size_t row0;
;                 if (u < 2048) { const int b = (u & 255) >> 5, c = u & 31, i = u >> 8; h = i >> 1; qblk = (i & 1) * 32 + c; row0 = (size_t)b * SP; S_ = SP; }
;                 else { const int v = u - 2048, b = (v & 255) >> 5, c = v & 31, idx = (v >> 8) * 32 + c; h = idx >> 4; qblk = idx & 15; row0 = (size_t)MP + (size_t)b * SS; S_ = SS; }
;                 U.q0 = 128 * qblk; U.h = h; U.NT = S_ / 64; U.ldk = NZ; U.mshift = mshA;
;                 U.Qb = Z + (row0 + U.q0) * NZ + 128 * h; U.Kb = Z + row0 * NZ + 512 + 128 * h; U.Vb = Z + row0 * NZ + 1024 + 128 * h; U.Ob = MIX + (row0 + U.q0) * DM + 128 * h;
;                 U.farL = SGPRF(lutA[h * att::LUTA_STRIDE + 0]); U.farR = SGPRF(lutA[h * att::LUTA_STRIDE + 640]);
;                 att::attn_unit<0>(U, (char*)lds, wave); }
.LBB0_305:
	s_waitcnt lgkmcnt(0)
	s_add_u32 s37, s16, 0xf400000
	s_addc_u32 s38, s17, 0
	s_add_u32 s39, s16, 0x28400000
	v_writelane_b32 v255, s16, 7
	s_addc_u32 s40, s17, 0
	s_add_i32 s90, 0, 0x1c000
	v_readlane_b32 s0, v254, 51
	v_mov_b32_e32 v0, s90
	s_nop 0
	v_mov_b32_e32 v4, s0
	s_barrier
	ds_read_b128 v[0:3], v0
	ds_read_b32 v4, v4
	v_readlane_b32 s0, v254, 10
	v_readlane_b32 s1, v254, 11
	v_writelane_b32 v255, s17, 8
	s_andn2_b64 vcc, exec, s[0:1]
	s_waitcnt lgkmcnt(0)
	v_readfirstlane_b32 s0, v4
	v_readfirstlane_b32 s11, v0
	v_readfirstlane_b32 s12, v1
	v_readfirstlane_b32 s13, v2
	v_readfirstlane_b32 s10, v3
	v_writelane_b32 v255, s0, 9
	s_cbranch_vccnz .LBB0_345
	v_readlane_b32 s0, v254, 2
	v_readlane_b32 s1, v255, 0
	s_nop 3
	s_cmp_ge_u32 s0, 0x80
	s_cselect_b32 s0, 1, 0
	s_cmp_eq_u32 s1, 0x100
	s_cselect_b32 s0, s0, 0
	v_mov_b32_e32 v0, 0x20208
	ds_read_b32 v1, v0
	s_waitcnt lgkmcnt(0)
	v_readfirstlane_b32 s1, v1
	s_nop 3
	s_cmp_eq_u32 s1, 0
	s_cselect_b32 s0, s0, 0
	s_cmp_eq_u32 s0, 1
	s_cbranch_scc0 .Lp2_pb_fall
	s_barrier
	v_mov_b32_e32 v1, 1
	ds_write_b32 v0, v1
	s_waitcnt lgkmcnt(0)
	s_barrier
	s_branch .LBB0_345
.Lp2_pb_fall:
	s_load_dwordx2 s[0:1], s[2:3], 0x60
	v_readlane_b32 s2, v255, 4
	v_readlane_b32 s3, v255, 5
	s_lshl_b32 s84, s2, 7
	s_lshl_b64 s[2:3], s[84:85], 2
	s_waitcnt lgkmcnt(0)
	s_add_u32 s4, s0, s2
	s_addc_u32 s5, s1, s3
	v_readlane_b32 s0, v255, 7
	v_readlane_b32 s1, v255, 8
	s_add_u32 s14, s0, 0xf4a0400
	s_addc_u32 s15, s1, 0
	v_readlane_b32 s16, v254, 2
	s_branch .LBB0_308

; __global__ void __launch_bounds__(NTHREADS, 2) hymba_fwd(Args args) {
;     ...
;                 att::attn_unit<0>(U, (char*)lds, wave); }
;             for (int u = vcu; u < 1280; u += G) {
;                 int seq, blk, p, R; size_t row0;
;                 if (u < 1024) { p = u & 1; blk = (u >> 1) & 63; seq = u >> 7; R = SP / GW; row0 = (size_t)seq * SP; }
;                 else { const int v = u - 1024; p = v & 1; blk = (v >> 1) & 15; seq = v >> 5; R = SS / GW; row0 = (size_t)MP + (size_t)seq * SS; }
;                 const int r0 = 2 * blk; int lo = r0 - 4; lo = lo < 0 ? 0 : lo; lo = lo > R - 8 ? R - 8 : lo; int hi2 = r0 + 1 - 4; hi2 = hi2 < 0 ? 0 : hi2; hi2 = hi2 > R - 8 ? R - 8 : hi2; hi2 += 7;
;                 U.q0 = r0; U.h = p; U.tile0 = lo; U.R = R; U.NT = ((hi2 - lo + 1) + 1) & ~1; U.ldk = NZ; U.mshift = mshB;
;                 U.Qb = Z + (row0 + 128 * blk) * NZ + 1536 + 128 * p; U.Kb = Z + row0 * NZ + 1792 + 128 * p; U.Vb = Z + row0 * NZ + 2048 + 128 * p; U.Ob = MIX + (row0 + 128 * blk) * DM + 512 + 128 * p;
;                 att::attn_unit<1>(U, (char*)lds, wave); }
.LBB0_345:
	v_mov_b32_e32 v0, 0x20208
	ds_read_b32 v1, v0
	s_waitcnt lgkmcnt(0)
	v_readfirstlane_b32 s0, v1
	s_nop 3
	s_cmp_eq_u32 s0, 2
	s_cbranch_scc0 .Lp2_pd_fall
	v_readlane_b32 s14, v252, 0
	v_readlane_b32 s18, v252, 1
	v_readlane_b32 s19, v252, 2
	v_readlane_b32 s20, v252, 3
	v_readlane_b32 s21, v252, 4
	v_readlane_b32 s22, v252, 5
	v_readlane_b32 s23, v252, 6
	v_readlane_b32 s24, v252, 7
	v_readlane_b32 s25, v252, 8
	v_readlane_b32 s28, v252, 9
	v_readlane_b32 s29, v252, 10
	v_readlane_b32 s36, v252, 11
	v_readlane_b32 s37, v252, 12
	v_readlane_b32 s42, v252, 13
	v_readlane_b32 s43, v252, 14
	v_readlane_b32 s50, v252, 15
	v_readlane_b32 s55, v252, 16
	v_readlane_b32 s56, v252, 17
	v_readlane_b32 s57, v252, 18
	v_readlane_b32 s58, v252, 19
	v_readlane_b32 s59, v252, 20
	v_readlane_b32 s60, v252, 21
	v_readlane_b32 s61, v252, 22
	v_readlane_b32 s62, v252, 23
	v_readlane_b32 s63, v252, 24
	v_readlane_b32 s67, v252, 25
	v_readlane_b32 s68, v252, 26
	v_readlane_b32 s69, v252, 27
	v_readlane_b32 s72, v252, 28
	v_readlane_b32 s73, v252, 29
	v_readlane_b32 s74, v252, 30
	v_readlane_b32 s75, v252, 31
	v_readlane_b32 s76, v252, 32
	v_readlane_b32 s77, v252, 33
	v_readlane_b32 s78, v252, 34
	v_readlane_b32 s79, v252, 35
	v_readlane_b32 s80, v252, 36
	v_readlane_b32 s81, v252, 37
	v_readlane_b32 s82, v252, 38
	v_readlane_b32 s83, v252, 39
	v_readlane_b32 s85, v252, 40
	v_readlane_b32 s90, v252, 41
	v_readlane_b32 s93, v252, 42
	v_readlane_b32 s94, v252, 43
	v_readlane_b32 s95, v252, 44
	v_readlane_b32 s96, v252, 45
	v_readlane_b32 s97, v252, 46
	s_nop 4
	s_barrier
	v_mov_b32_e32 v1, 0
	ds_write_b32 v0, v1
	s_waitcnt lgkmcnt(0)
	s_barrier
	s_branch .LBB0_636

; #define GRID_BAR() do { CArgsP apb_ = (CArgsP)__builtin_amdgcn_kernarg_segment_ptr(); asm volatile("" : "+s"(apb_)); XcdBarrier b_; b_.bar = (unsigned*)(apb_->ws + WS_BAR); b_.x = xb_xcc_id(); \
;         b_.st = (volatile LAS unsigned*)((LAS unsigned char*)lds + OFF_BARST); xcd_barrier(b_, fresh_tid(wave) == 0); } while (0)
; __global__ void __launch_bounds__(NTHREADS, 2) hymba_fwd(Args args) {
;     ...
;             for (int u = vcu; u < 1280; u += G) { const int p = u & 1, blk = u >> 1; const size_t row = (size_t)blk * 128;
;                 const int mb = row < MP ? (int)(row / SP) : NBATCH + (int)((row - MP) / SS);
;                 U.NT = MEMT / 64; U.ldk = 512; U.h = p; U.q0 = 0; U.mshift = mshC;
;                 U.Qb = Z + row * NZ + 2304 + 128 * p; U.Kb = MKV + (size_t)mb * MEMT * 512 + 128 * p; U.Vb = MKV + (size_t)mb * MEMT * 512 + 256 + 128 * p; U.Ob = MIX + row * DM + 768 + 128 * p;
;                 att::attn_unit<2>(U, (char*)lds, wave); }
;         }
;         GRID_BAR();
.LBB0_636:
	v_mov_b32_e32 v0, 0x20208
	ds_read_b32 v1, v0
	s_waitcnt lgkmcnt(0)
	v_readfirstlane_b32 s0, v1
	s_nop 3
	s_cmp_eq_u32 s0, 1
	s_cbranch_scc0 .Lp2_pc_fall
	v_writelane_b32 v252, s14, 0
	v_writelane_b32 v252, s18, 1
	v_writelane_b32 v252, s19, 2
	v_writelane_b32 v252, s20, 3
	v_writelane_b32 v252, s21, 4
	v_writelane_b32 v252, s22, 5
	v_writelane_b32 v252, s23, 6
	v_writelane_b32 v252, s24, 7
	v_writelane_b32 v252, s25, 8
	v_writelane_b32 v252, s28, 9
	v_writelane_b32 v252, s29, 10
	v_writelane_b32 v252, s36, 11
	v_writelane_b32 v252, s37, 12
	v_writelane_b32 v252, s42, 13
	v_writelane_b32 v252, s43, 14
	v_writelane_b32 v252, s50, 15
	v_writelane_b32 v252, s55, 16
	v_writelane_b32 v252, s56, 17
	v_writelane_b32 v252, s57, 18
	v_writelane_b32 v252, s58, 19
	v_writelane_b32 v252, s59, 20
	v_writelane_b32 v252, s60, 21
	v_writelane_b32 v252, s61, 22
	v_writelane_b32 v252, s62, 23
	v_writelane_b32 v252, s63, 24
	v_writelane_b32 v252, s67, 25
	v_writelane_b32 v252, s68, 26
	v_writelane_b32 v252, s69, 27
	v_writelane_b32 v252, s72, 28
	v_writelane_b32 v252, s73, 29
	v_writelane_b32 v252, s74, 30
	v_writelane_b32 v252, s75, 31
	v_writelane_b32 v252, s76, 32
	v_writelane_b32 v252, s77, 33
	v_writelane_b32 v252, s78, 34
	v_writelane_b32 v252, s79, 35
	v_writelane_b32 v252, s80, 36
	v_writelane_b32 v252, s81, 37
	v_writelane_b32 v252, s82, 38
	v_writelane_b32 v252, s83, 39
	v_writelane_b32 v252, s85, 40
	v_writelane_b32 v252, s90, 41
	v_writelane_b32 v252, s93, 42
	v_writelane_b32 v252, s94, 43
	v_writelane_b32 v252, s95, 44
	v_writelane_b32 v252, s96, 45
	v_writelane_b32 v252, s97, 46
	s_barrier
	v_mov_b32_e32 v1, 2
	ds_write_b32 v0, v1
	s_waitcnt lgkmcnt(0)
	s_barrier
	s_branch .Lp2_reenter
